# load de-serialisation: LayerNorm row loops issue all four row loads before the first wait
# speedup vs baseline: 1.0059x; 1.0002x over previous
; DI void ln_phase(const float* S, const float* __restrict__ g, const float* __restrict__ b, u16* XBo, float* fout) {
;     ...
;   for (int row = wave; row < NT; row += nw) {
;     float4 v[4];
;     float s = 0.f;
; #pragma unroll
;     for (int i = 0; i < 4; ++i) { v[i] = *(const float4*)(S + (size_t)row * 1024 + i * 256 + l * 4); s += v[i].x + v[i].y + v[i].z + v[i].w; }
; #pragma unroll
;     for (int o = 32; o; o >>= 1) s += __shfl_xor(s, o);
;     const float mu = s * (1.f / 1024.f);
;     float q = 0.f;
; #pragma unroll
;     for (int i = 0; i < 4; ++i) { float a = v[i].x - mu, bb = v[i].y - mu, c = v[i].z - mu, d = v[i].w - mu; q += a * a + bb * bb + c * c + d * d; }
; #pragma unroll
;     for (int o = 32; o; o >>= 1) q += __shfl_xor(q, o);
;     const float rs = rsqrtf(q * (1.f / 1024.f) + EPS);
; #pragma unroll
;     for (int i = 0; i < 4; ++i) {
;       const int c = i * 256 + l * 4;
;       const float4 gg = *(const float4*)(g + c), bb = *(const float4*)(b + c);
;       float4 y;
;       y.x = (v[i].x - mu) * rs * gg.x + bb.x; y.y = (v[i].y - mu) * rs * gg.y + bb.y;
;       y.z = (v[i].z - mu) * rs * gg.z + bb.z; y.w = (v[i].w - mu) * rs * gg.w + bb.w;
;       if (fout) *(float4*)(fout + (size_t)row * 1024 + c) = y;
;       if (XBo) { uint2 o; o.x = pack2(y.x, y.y); o.y = pack2(y.z, y.w); *(uint2*)(XBo + (size_t)row * LDX + c) = o; }
;     }
.LBB0_740:
	global_load_dwordx4 v[46:49], v[38:39], off offset:2048
	global_load_dwordx4 v[50:53], v[38:39], off offset:3072
	global_load_dwordx4 v[54:57], v[38:39], off
	global_load_dwordx4 v[58:61], v[38:39], off offset:1024
	v_mov_b32_e32 v68, v1
	v_add_u32_e32 v34, s2, v34
	s_waitcnt vmcnt(3)
	v_mov_b32_e32 v72, v46
	s_waitcnt vmcnt(2)
	v_mov_b32_e32 v73, v50
	v_mov_b32_e32 v74, v47
	v_mov_b32_e32 v75, v51
	v_mov_b32_e32 v76, v48
	v_mov_b32_e32 v77, v52
	v_pk_add_f32 v[72:73], v[72:73], v[74:75]
	v_mov_b32_e32 v78, v49
	v_mov_b32_e32 v79, v53
	v_pk_add_f32 v[72:73], v[72:73], v[76:77]
	s_nop 0
	v_pk_add_f32 v[62:63], v[72:73], v[78:79]
	v_lshl_add_u64 v[38:39], v[38:39], 0, s[6:7]
	s_waitcnt vmcnt(1)
	v_mov_b32_e32 v0, v55
	v_pk_add_f32 v[64:65], v[54:55], v[0:1]
	v_mov_b32_e32 v70, v56
	s_waitcnt vmcnt(0)
	v_mov_b32_e32 v65, v58
	v_mov_b32_e32 v71, v59
	v_pk_mov_b32 v[66:67], v[56:57], v[60:61] op_sel:[1,0]
	v_pk_add_f32 v[64:65], v[64:65], v[70:71]
	v_mov_b32_e32 v69, v61
	v_pk_add_f32 v[64:65], v[64:65], v[66:67]
	s_nop 0
	v_pk_add_f32 v[64:65], v[64:65], v[68:69]
	s_nop 0
	v_add_f32_e32 v0, v64, v65
	v_add_f32_e32 v0, v0, v62
	v_add_f32_e32 v0, v0, v63
	ds_bpermute_b32 v35, v40, v0
	s_waitcnt lgkmcnt(0)
	v_add_f32_e32 v0, v0, v35
	ds_bpermute_b32 v35, v41, v0
	s_waitcnt lgkmcnt(0)
	v_add_f32_e32 v0, v0, v35
	ds_bpermute_b32 v35, v42, v0
	s_waitcnt lgkmcnt(0)
	v_add_f32_e32 v0, v0, v35
	ds_bpermute_b32 v35, v43, v0
	s_waitcnt lgkmcnt(0)
	v_add_f32_e32 v0, v0, v35
	ds_bpermute_b32 v35, v44, v0
	s_waitcnt lgkmcnt(0)
	v_add_f32_e32 v0, v0, v35
	ds_bpermute_b32 v35, v45, v0
	s_waitcnt lgkmcnt(0)
	v_add_f32_e32 v0, v0, v35
	v_mul_f32_e32 v0, 0x3a800000, v0
	v_pk_add_f32 v[54:55], v[54:55], v[0:1] op_sel_hi:[1,0] neg_lo:[0,1] neg_hi:[0,1]
	v_pk_add_f32 v[58:59], v[58:59], v[0:1] op_sel_hi:[1,0] neg_lo:[0,1] neg_hi:[0,1]
	v_mov_b32_e32 v64, v55
	v_mov_b32_e32 v65, v59
	v_pk_add_f32 v[56:57], v[56:57], v[0:1] op_sel_hi:[1,0] neg_lo:[0,1] neg_hi:[0,1]
	v_pk_add_f32 v[60:61], v[60:61], v[0:1] op_sel_hi:[1,0] neg_lo:[0,1] neg_hi:[0,1]
	v_mov_b32_e32 v62, v54
	v_mov_b32_e32 v63, v58
	v_pk_mul_f32 v[64:65], v[64:65], v[64:65]
	v_pk_add_f32 v[46:47], v[46:47], v[0:1] op_sel_hi:[1,0] neg_lo:[0,1] neg_hi:[0,1]
	v_pk_add_f32 v[50:51], v[50:51], v[0:1] op_sel_hi:[1,0] neg_lo:[0,1] neg_hi:[0,1]
	v_pk_fma_f32 v[62:63], v[62:63], v[62:63], v[64:65]
	v_mov_b32_e32 v64, v56
	v_mov_b32_e32 v65, v60
	v_mov_b32_e32 v70, v51
	v_mov_b32_e32 v71, v47
	v_pk_fma_f32 v[62:63], v[64:65], v[64:65], v[62:63]
	v_mov_b32_e32 v64, v57
	v_mov_b32_e32 v65, v61
	v_pk_add_f32 v[48:49], v[48:49], v[0:1] op_sel_hi:[1,0] neg_lo:[0,1] neg_hi:[0,1]
	v_pk_add_f32 v[52:53], v[52:53], v[0:1] op_sel_hi:[1,0] neg_lo:[0,1] neg_hi:[0,1]
	v_mov_b32_e32 v68, v50
	v_mov_b32_e32 v69, v46
	v_pk_mul_f32 v[70:71], v[70:71], v[70:71]
	v_pk_fma_f32 v[62:63], v[64:65], v[64:65], v[62:63]
	v_mov_b32_e32 v64, v52
	v_mov_b32_e32 v65, v48
	v_pk_fma_f32 v[68:69], v[68:69], v[68:69], v[70:71]
	v_mov_b32_e32 v66, v53
	v_mov_b32_e32 v67, v49
	v_pk_fma_f32 v[64:65], v[64:65], v[64:65], v[68:69]
	v_add_f32_e32 v0, v62, v63
	v_pk_fma_f32 v[64:65], v[66:67], v[66:67], v[64:65]
	s_nop 0
	v_add_f32_e32 v0, v65, v0
	v_add_f32_e32 v0, v64, v0
	ds_bpermute_b32 v35, v40, v0
	s_waitcnt lgkmcnt(0)
	v_add_f32_e32 v0, v0, v35
	ds_bpermute_b32 v35, v41, v0
	s_waitcnt lgkmcnt(0)
	v_add_f32_e32 v0, v0, v35
	ds_bpermute_b32 v35, v42, v0
	s_waitcnt lgkmcnt(0)
	v_add_f32_e32 v0, v0, v35
	ds_bpermute_b32 v35, v43, v0
	s_waitcnt lgkmcnt(0)
	v_add_f32_e32 v0, v0, v35
	ds_bpermute_b32 v35, v44, v0
	s_waitcnt lgkmcnt(0)
	v_add_f32_e32 v0, v0, v35
	ds_bpermute_b32 v35, v45, v0
	s_waitcnt lgkmcnt(0)
	v_add_f32_e32 v0, v0, v35
	v_fmamk_f32 v0, v0, 0x3a800000, v170
	v_cmp_gt_f32_e32 vcc, s62, v0
	v_mul_f32_e32 v35, 0x4b800000, v0
	s_nop 0
	v_cndmask_b32_e32 v0, v0, v35, vcc
	v_rsq_f32_e32 v0, v0
	s_nop 0
	v_mul_f32_e32 v35, 0x45800000, v0
	v_cndmask_b32_e32 v0, v0, v35, vcc
	v_pk_mul_f32 v[54:55], v[54:55], v[0:1] op_sel_hi:[1,0]
	v_pk_mul_f32 v[56:57], v[56:57], v[0:1] op_sel_hi:[1,0]
	v_pk_mul_f32 v[46:47], v[46:47], v[0:1] op_sel_hi:[1,0]
	v_pk_mul_f32 v[48:49], v[48:49], v[0:1] op_sel_hi:[1,0]
	v_pk_fma_f32 v[54:55], v[2:3], v[54:55], v[10:11]
	v_pk_fma_f32 v[56:57], v[4:5], v[56:57], v[12:13]
	v_pk_fma_f32 v[46:47], v[18:19], v[46:47], v[26:27]
	v_pk_fma_f32 v[48:49], v[20:21], v[48:49], v[28:29]
	v_cvt_pk_bf16_f32 v54, v54, v55
	v_cvt_pk_bf16_f32 v55, v56, v57
	v_cvt_pk_bf16_f32 v46, v46, v47
	v_cvt_pk_bf16_f32 v47, v48, v49
	global_store_dwordx2 v[36:37], v[54:55], off
	v_pk_mul_f32 v[54:55], v[58:59], v[0:1] op_sel_hi:[1,0]
	v_pk_mul_f32 v[56:57], v[60:61], v[0:1] op_sel_hi:[1,0]
	global_store_dwordx2 v[36:37], v[46:47], off offset:1024
	v_pk_mul_f32 v[46:47], v[50:51], v[0:1] op_sel_hi:[1,0]
	v_pk_mul_f32 v[48:49], v[52:53], v[0:1] op_sel_hi:[1,0]
	v_pk_fma_f32 v[54:55], v[6:7], v[54:55], v[14:15]
	v_pk_fma_f32 v[56:57], v[8:9], v[56:57], v[16:17]
	v_pk_fma_f32 v[46:47], v[22:23], v[46:47], v[30:31]
	v_pk_fma_f32 v[48:49], v[24:25], v[48:49], v[32:33]
	v_cvt_pk_bf16_f32 v54, v54, v55
	v_cvt_pk_bf16_f32 v55, v56, v57
	v_cvt_pk_bf16_f32 v46, v46, v47
	v_cvt_pk_bf16_f32 v47, v48, v49
	v_cmp_lt_i32_e32 vcc, s24, v34
	global_store_dwordx2 v[36:37], v[54:55], off offset:512
	global_store_dwordx2 v[36:37], v[46:47], off offset:1536
	v_lshl_add_u64 v[36:37], v[36:37], 0, s[4:5]
	s_or_b64 s[8:9], vcc, s[8:9]
	s_andn2_b64 exec, exec, s[8:9]
	s_cbranch_execnz .LBB0_740

; DI void ln_phase(const float* S, const float* __restrict__ g, const float* __restrict__ b, u16* XBo, float* fout) {
;     ...
;   for (int row = wave; row < NT; row += nw) {
;     float4 v[4];
;     float s = 0.f;
; #pragma unroll
;     for (int i = 0; i < 4; ++i) { v[i] = *(const float4*)(S + (size_t)row * 1024 + i * 256 + l * 4); s += v[i].x + v[i].y + v[i].z + v[i].w; }
; #pragma unroll
;     for (int o = 32; o; o >>= 1) s += __shfl_xor(s, o);
;     const float mu = s * (1.f / 1024.f);
;     float q = 0.f;
; #pragma unroll
;     for (int i = 0; i < 4; ++i) { float a = v[i].x - mu, bb = v[i].y - mu, c = v[i].z - mu, d = v[i].w - mu; q += a * a + bb * bb + c * c + d * d; }
; #pragma unroll
;     for (int o = 32; o; o >>= 1) q += __shfl_xor(q, o);
;     const float rs = rsqrtf(q * (1.f / 1024.f) + EPS);
; #pragma unroll
;     for (int i = 0; i < 4; ++i) {
;       const int c = i * 256 + l * 4;
;       const float4 gg = *(const float4*)(g + c), bb = *(const float4*)(b + c);
;       float4 y;
;       y.x = (v[i].x - mu) * rs * gg.x + bb.x; y.y = (v[i].y - mu) * rs * gg.y + bb.y;
;       y.z = (v[i].z - mu) * rs * gg.z + bb.z; y.w = (v[i].w - mu) * rs * gg.w + bb.w;
;       if (fout) *(float4*)(fout + (size_t)row * 1024 + c) = y;
;       if (XBo) { uint2 o; o.x = pack2(y.x, y.y); o.y = pack2(y.z, y.w); *(uint2*)(XBo + (size_t)row * LDX + c) = o; }
.LBB0_825:
	v_lshl_add_u64 v[46:47], v[44:45], 0, v[0:1]
	global_load_dwordx4 v[34:37], v[46:47], off offset:3072
	global_load_dwordx4 v[50:53], v[46:47], off offset:2048
	global_load_dwordx4 v[54:57], v[46:47], off offset:1024
	s_nop 0
	global_load_dwordx4 v[46:49], v[46:47], off
	s_waitcnt vmcnt(3)
	v_mov_b32_e32 v73, v34
	s_waitcnt vmcnt(2)
	v_mov_b32_e32 v72, v50
	v_mov_b32_e32 v74, v51
	v_mov_b32_e32 v75, v35
	v_pk_add_f32 v[72:73], v[72:73], v[74:75]
	v_mov_b32_e32 v74, v52
	v_mov_b32_e32 v75, v36
	v_pk_add_f32 v[72:73], v[72:73], v[74:75]
	v_mov_b32_e32 v74, v53
	v_mov_b32_e32 v75, v37
	v_pk_add_f32 v[58:59], v[72:73], v[74:75]
	s_waitcnt vmcnt(1)
	v_mov_b32_e32 v61, v54
	s_waitcnt vmcnt(0)
	v_mov_b32_e32 v60, v46
	v_mov_b32_e32 v68, v47
	v_mov_b32_e32 v69, v55
	v_pk_add_f32 v[60:61], v[60:61], v[68:69]
	v_mov_b32_e32 v68, v48
	v_mov_b32_e32 v69, v56
	v_pk_add_f32 v[60:61], v[60:61], v[68:69]
	v_mov_b32_e32 v68, v49
	v_mov_b32_e32 v69, v57
	v_pk_add_f32 v[60:61], v[60:61], v[68:69]
	s_nop 0
	v_add_f32_e32 v39, 0, v60
	v_add_f32_e32 v39, v39, v61
	v_add_f32_e32 v39, v39, v58
	v_add_f32_e32 v39, v39, v59
	ds_bpermute_b32 v58, v62, v39
	s_waitcnt lgkmcnt(0)
	v_add_f32_e32 v39, v39, v58
	ds_bpermute_b32 v58, v63, v39
	s_waitcnt lgkmcnt(0)
	v_add_f32_e32 v39, v39, v58
	ds_bpermute_b32 v58, v64, v39
	s_waitcnt lgkmcnt(0)
	v_add_f32_e32 v39, v39, v58
	ds_bpermute_b32 v58, v65, v39
	s_waitcnt lgkmcnt(0)
	v_add_f32_e32 v39, v39, v58
	ds_bpermute_b32 v58, v66, v39
	s_waitcnt lgkmcnt(0)
	v_add_f32_e32 v39, v39, v58
	ds_bpermute_b32 v58, v67, v39
	s_waitcnt lgkmcnt(0)
	v_add_f32_e32 v39, v39, v58
	v_mul_f32_e32 v58, 0x3a800000, v39
	v_pk_add_f32 v[60:61], v[46:47], v[58:59] op_sel_hi:[1,0] neg_lo:[0,1] neg_hi:[0,1]
	v_pk_add_f32 v[68:69], v[48:49], v[58:59] op_sel_hi:[1,0] neg_lo:[0,1] neg_hi:[0,1]
	v_pk_add_f32 v[48:49], v[54:55], v[58:59] op_sel_hi:[1,0] neg_lo:[0,1] neg_hi:[0,1]
	v_pk_add_f32 v[46:47], v[56:57], v[58:59] op_sel_hi:[1,0] neg_lo:[0,1] neg_hi:[0,1]
	v_mov_b32_e32 v56, v61
	v_mov_b32_e32 v57, v49
	v_mov_b32_e32 v54, v60
	v_mov_b32_e32 v55, v48
	v_pk_mul_f32 v[56:57], v[56:57], v[56:57]
	v_cndmask_b32_e64 v39, 0, 1, s[10:11]
	v_pk_fma_f32 v[54:55], v[54:55], v[54:55], v[56:57]
	v_mov_b32_e32 v56, v68
	v_mov_b32_e32 v57, v46
	v_pk_fma_f32 v[54:55], v[56:57], v[56:57], v[54:55]
	v_mov_b32_e32 v56, v69
	v_mov_b32_e32 v57, v47
	v_pk_fma_f32 v[70:71], v[56:57], v[56:57], v[54:55]
	v_pk_add_f32 v[56:57], v[50:51], v[58:59] op_sel_hi:[1,0] neg_lo:[0,1] neg_hi:[0,1]
	v_pk_add_f32 v[54:55], v[52:53], v[58:59] op_sel_hi:[1,0] neg_lo:[0,1] neg_hi:[0,1]
	v_pk_add_f32 v[52:53], v[34:35], v[58:59] op_sel_hi:[1,0] neg_lo:[0,1] neg_hi:[0,1]
	v_pk_add_f32 v[50:51], v[36:37], v[58:59] op_sel_hi:[1,0] neg_lo:[0,1] neg_hi:[0,1]
	v_mov_b32_e32 v36, v53
	v_mov_b32_e32 v37, v57
	v_mov_b32_e32 v34, v52
	v_mov_b32_e32 v35, v56
	v_pk_mul_f32 v[36:37], v[36:37], v[36:37]
	v_cmp_ne_u32_e64 s[0:1], 1, v39
	v_pk_fma_f32 v[34:35], v[34:35], v[34:35], v[36:37]
	v_mov_b32_e32 v36, v50
	v_mov_b32_e32 v37, v54
	v_pk_fma_f32 v[34:35], v[36:37], v[36:37], v[34:35]
	v_mov_b32_e32 v36, v51
	v_mov_b32_e32 v37, v55
	v_pk_fma_f32 v[34:35], v[36:37], v[36:37], v[34:35]
	v_add_f32_e32 v36, v70, v71
	v_add_f32_e32 v35, v35, v36
	v_add_f32_e32 v34, v34, v35
	ds_bpermute_b32 v35, v62, v34
	s_waitcnt lgkmcnt(0)
	v_add_f32_e32 v34, v34, v35
	ds_bpermute_b32 v35, v63, v34
	s_waitcnt lgkmcnt(0)
	v_add_f32_e32 v34, v34, v35
	ds_bpermute_b32 v35, v64, v34
	s_waitcnt lgkmcnt(0)
	v_add_f32_e32 v34, v34, v35
	ds_bpermute_b32 v35, v65, v34
	s_waitcnt lgkmcnt(0)
	v_add_f32_e32 v34, v34, v35
	ds_bpermute_b32 v35, v66, v34
	s_waitcnt lgkmcnt(0)
	v_add_f32_e32 v34, v34, v35
	ds_bpermute_b32 v35, v67, v34
	s_waitcnt lgkmcnt(0)
	v_add_f32_e32 v34, v34, v35
	v_fmamk_f32 v34, v34, 0x3a800000, v170
	v_cmp_gt_f32_e32 vcc, s62, v34
	v_mul_f32_e32 v35, 0x4b800000, v34
	s_nop 0
	v_cndmask_b32_e32 v34, v34, v35, vcc
	v_rsq_f32_e32 v34, v34
	s_nop 0
	v_mul_f32_e32 v35, 0x45800000, v34
	v_cndmask_b32_e32 v58, v34, v35, vcc
	v_pk_mul_f32 v[34:35], v[60:61], v[58:59] op_sel_hi:[1,0]
	v_pk_mul_f32 v[36:37], v[68:69], v[58:59] op_sel_hi:[1,0]
	v_pk_fma_f32 v[34:35], v[2:3], v[34:35], v[10:11]
	v_pk_fma_f32 v[36:37], v[4:5], v[36:37], v[12:13]
	s_andn2_b64 vcc, exec, s[10:11]
	v_lshl_add_u64 v[60:61], v[40:41], 0, v[0:1]
	s_cbranch_vccnz .LBB0_827
	global_store_dwordx4 v[60:61], v[34:37], off
